# speedup vs baseline: 1.0108x; 1.0108x over previous
.LBB0_1769:
	s_or_b64 exec, exec, s[0:1]
	s_mov_b32 s0, 0x408000
	v_cmp_gt_i32_e32 vcc, s0, v0
	s_and_saveexec_b64 s[0:1], vcc
	s_cbranch_execz .LBB0_1772
	v_lshrrev_b32_e32 v2, 2, v6
	v_and_b32_e32 v1, 0x1ff, v6
	s_waitcnt vmcnt(10)
	v_and_b32_e32 v8, 0x7c, v2
	v_mov_b32_e32 v9, 0
	v_lshl_add_u64 v[2:3], s[90:91], 0, v[8:9]
	s_mov_b64 s[2:3], 0x2a4b0000
	v_lshlrev_b32_e32 v8, 4, v1
	v_lshl_add_u64 v[2:3], v[2:3], 0, s[2:3]
	v_lshl_add_u64 v[6:7], s[90:91], 0, v[8:9]
	s_mov_b64 s[2:3], 0x32a30000
	v_lshl_add_u64 v[4:5], v[6:7], 0, s[2:3]
	s_mov_b64 s[2:3], 0x22230000
	v_lshl_add_u64 v[6:7], v[6:7], 0, s[2:3]
	v_lshl_add_u64 v[8:9], s[80:81], 0, v[8:9]
	s_mov_b64 s[2:3], 0
	s_mov_b64 s[4:5], 0x2100
	s_mov_b64 s[6:7], 0x4200
	s_mov_b32 s9, 0x407fff
	s_waitcnt vmcnt(0)
.Lmg_top:
	v_readfirstlane_b32 s10, v0
	s_nop 3
	s_add_i32 s10, s10, s12
	s_cmp_gt_i32 s10, s9
	s_cbranch_scc1 .Lmg_tail
	v_ashrrev_i32_e32 v10, 9, v0
	v_ashrrev_i32_e32 v11, 31, v10
	v_lshlrev_b64 v[12:13], 7, v[10:11]
	v_lshl_add_u64 v[14:15], v[10:11], 0, s[4:5]
	v_lshl_add_u64 v[16:17], v[10:11], 0, s[6:7]
	v_lshlrev_b64 v[10:11], 13, v[10:11]
	v_lshl_add_u64 v[26:27], v[2:3], 0, v[12:13]
	v_lshlrev_b64 v[18:19], 7, v[14:15]
	v_lshlrev_b64 v[20:21], 7, v[16:17]
	v_lshlrev_b64 v[14:15], 13, v[14:15]
	v_lshlrev_b64 v[16:17], 13, v[16:17]
	v_lshl_add_u64 v[12:13], v[6:7], 0, v[10:11]
	v_lshl_add_u64 v[28:29], v[4:5], 0, v[10:11]
	v_lshl_add_u64 v[30:31], v[8:9], 0, v[10:11]
	global_load_dwordx4 v[10:13], v[12:13], off
	v_lshl_add_u64 v[32:33], v[2:3], 0, v[18:19]
	v_lshl_add_u64 v[34:35], v[2:3], 0, v[20:21]
	v_lshl_add_u64 v[36:37], v[4:5], 0, v[14:15]
	v_lshl_add_u64 v[38:39], v[4:5], 0, v[16:17]
	global_load_dword v1, v[26:27], off
	global_load_dword v46, v[32:33], off
	global_load_dword v47, v[34:35], off
	global_load_dwordx4 v[14:17], v[28:29], off
	global_load_dwordx4 v[18:21], v[36:37], off
	global_load_dwordx4 v[22:25], v[38:39], off
	v_add_u32_e32 v60, s12, v0
	v_ashrrev_i32_e32 v70, 9, v60
	v_ashrrev_i32_e32 v71, 31, v70
	v_lshlrev_b64 v[72:73], 7, v[70:71]
	v_lshl_add_u64 v[74:75], v[70:71], 0, s[4:5]
	v_lshl_add_u64 v[76:77], v[70:71], 0, s[6:7]
	v_lshlrev_b64 v[70:71], 13, v[70:71]
	v_lshl_add_u64 v[86:87], v[2:3], 0, v[72:73]
	v_lshlrev_b64 v[78:79], 7, v[74:75]
	v_lshlrev_b64 v[80:81], 7, v[76:77]
	v_lshlrev_b64 v[74:75], 13, v[74:75]
	v_lshlrev_b64 v[76:77], 13, v[76:77]
	v_lshl_add_u64 v[72:73], v[6:7], 0, v[70:71]
	v_lshl_add_u64 v[88:89], v[4:5], 0, v[70:71]
	v_lshl_add_u64 v[90:91], v[8:9], 0, v[70:71]
	global_load_dwordx4 v[70:73], v[72:73], off
	v_lshl_add_u64 v[92:93], v[2:3], 0, v[78:79]
	v_lshl_add_u64 v[94:95], v[2:3], 0, v[80:81]
	v_lshl_add_u64 v[96:97], v[4:5], 0, v[74:75]
	v_lshl_add_u64 v[98:99], v[4:5], 0, v[76:77]
	global_load_dword v61, v[86:87], off
	global_load_dword v106, v[92:93], off
	global_load_dword v107, v[94:95], off
	global_load_dwordx4 v[74:77], v[88:89], off
	global_load_dwordx4 v[78:81], v[96:97], off
	global_load_dwordx4 v[82:85], v[98:99], off
	v_add_u32_e32 v0, s12, v60
	s_waitcnt vmcnt(13)
	v_and_b32_e32 v27, 0xffff0000, v10
	v_lshlrev_b32_e32 v26, 16, v10
	s_waitcnt vmcnt(10)
	v_max3_f32 v48, v1, v46, v47
	v_sub_f32_e32 v1, v1, v48
	v_and_b32_e32 v29, 0xffff0000, v11
	s_waitcnt vmcnt(7)
	v_and_b32_e32 v43, 0xffff0000, v24
	v_lshlrev_b32_e32 v42, 16, v24
	v_sub_f32_e32 v24, v46, v48
	v_lshlrev_b32_e32 v28, 16, v11
	v_and_b32_e32 v11, 0xffff0000, v12
	v_lshlrev_b32_e32 v10, 16, v12
	v_and_b32_e32 v33, 0xffff0000, v13
	v_lshlrev_b32_e32 v32, 16, v13
	v_and_b32_e32 v13, 0xffff0000, v14
	v_lshlrev_b32_e32 v12, 16, v18
	v_and_b32_e32 v35, 0xffff0000, v18
	v_lshlrev_b32_e32 v34, 16, v14
	v_and_b32_e32 v37, 0xffff0000, v22
	v_lshlrev_b32_e32 v36, 16, v22
	v_and_b32_e32 v39, 0xffff0000, v15
	v_lshlrev_b32_e32 v18, 16, v15
	v_and_b32_e32 v15, 0xffff0000, v23
	v_lshlrev_b32_e32 v14, 16, v23
	v_and_b32_e32 v23, 0xffff0000, v16
	v_lshlrev_b32_e32 v22, 16, v20
	v_and_b32_e32 v41, 0xffff0000, v20
	v_lshlrev_b32_e32 v40, 16, v16
	v_and_b32_e32 v45, 0xffff0000, v17
	v_lshlrev_b32_e32 v20, 16, v17
	v_and_b32_e32 v17, 0xffff0000, v25
	v_lshlrev_b32_e32 v16, 16, v25
	v_sub_f32_e32 v25, v47, v48
	v_mul_f32_e32 v1, 0x3fb8aa3b, v1
	v_mul_f32_e32 v24, 0x3fb8aa3b, v24
	v_mul_f32_e32 v46, 0x3fb8aa3b, v25
	v_exp_f32_e32 v25, v1
	v_exp_f32_e32 v24, v24
	v_exp_f32_e32 v1, v46
	v_lshlrev_b32_e32 v38, 16, v19
	v_and_b32_e32 v19, 0xffff0000, v19
	v_add_f32_e32 v46, v25, v24
	v_add_f32_e32 v46, v1, v46
	v_div_scale_f32 v47, s[10:11], v46, v46, 1.0
	v_rcp_f32_e32 v49, v47
	v_div_scale_f32 v48, vcc, 1.0, v46, 1.0
	v_lshlrev_b32_e32 v44, 16, v21
	v_fma_f32 v50, -v47, v49, 1.0
	v_fmac_f32_e32 v49, v50, v49
	v_mul_f32_e32 v50, v48, v49
	v_fma_f32 v51, -v47, v50, v48
	v_fmac_f32_e32 v50, v51, v49
	v_fma_f32 v47, -v47, v50, v48
	v_div_fmas_f32 v47, v47, v49, v50
	v_div_fixup_f32 v46, v47, v46, 1.0
	v_and_b32_e32 v21, 0xffff0000, v21
	v_pk_mul_f32 v[24:25], v[24:25], v[46:47] op_sel_hi:[1,0]
	v_mul_f32_e32 v48, v1, v46
	v_pk_mul_f32 v[34:35], v[24:25], v[34:35] op_sel:[1,0] op_sel_hi:[0,1]
	v_pk_mul_f32 v[18:19], v[24:25], v[18:19] op_sel:[1,0] op_sel_hi:[0,1]
	v_pk_mul_f32 v[40:41], v[24:25], v[40:41] op_sel:[1,0] op_sel_hi:[0,1]
	v_pk_mul_f32 v[20:21], v[24:25], v[20:21] op_sel:[1,0] op_sel_hi:[0,1]
	v_pk_fma_f32 v[12:13], v[24:25], v[12:13], v[34:35]
	v_pk_fma_f32 v[18:19], v[24:25], v[38:39], v[18:19]
	v_pk_fma_f32 v[22:23], v[24:25], v[22:23], v[40:41]
	v_pk_fma_f32 v[20:21], v[24:25], v[44:45], v[20:21]
	v_pk_fma_f32 v[12:13], v[48:49], v[36:37], v[12:13] op_sel_hi:[0,1,1]
	v_pk_fma_f32 v[14:15], v[48:49], v[14:15], v[18:19] op_sel_hi:[0,1,1]
	v_pk_fma_f32 v[18:19], v[48:49], v[42:43], v[22:23] op_sel_hi:[0,1,1]
	v_pk_fma_f32 v[16:17], v[48:49], v[16:17], v[20:21] op_sel_hi:[0,1,1]
	v_pk_mul_f32 v[12:13], v[12:13], v[26:27]
	v_pk_mul_f32 v[14:15], v[14:15], v[28:29]
	v_pk_mul_f32 v[18:19], v[18:19], v[10:11]
	v_pk_mul_f32 v[16:17], v[16:17], v[32:33]
	v_cvt_pk_bf16_f32 v10, v12, v13
	v_cvt_pk_bf16_f32 v11, v14, v15
	v_cvt_pk_bf16_f32 v12, v18, v19
	v_cvt_pk_bf16_f32 v13, v16, v17
	global_store_dwordx4 v[30:31], v[10:13], off
	s_waitcnt vmcnt(6)
	v_and_b32_e32 v87, 0xffff0000, v70
	v_lshlrev_b32_e32 v86, 16, v70
	s_waitcnt vmcnt(3)
	v_max3_f32 v108, v61, v106, v107
	v_sub_f32_e32 v61, v61, v108
	v_and_b32_e32 v89, 0xffff0000, v71
	s_waitcnt vmcnt(0)
	v_and_b32_e32 v103, 0xffff0000, v84
	v_lshlrev_b32_e32 v102, 16, v84
	v_sub_f32_e32 v84, v106, v108
	v_lshlrev_b32_e32 v88, 16, v71
	v_and_b32_e32 v71, 0xffff0000, v72
	v_lshlrev_b32_e32 v70, 16, v72
	v_and_b32_e32 v93, 0xffff0000, v73
	v_lshlrev_b32_e32 v92, 16, v73
	v_and_b32_e32 v73, 0xffff0000, v74
	v_lshlrev_b32_e32 v72, 16, v78
	v_and_b32_e32 v95, 0xffff0000, v78
	v_lshlrev_b32_e32 v94, 16, v74
	v_and_b32_e32 v97, 0xffff0000, v82
	v_lshlrev_b32_e32 v96, 16, v82
	v_and_b32_e32 v99, 0xffff0000, v75
	v_lshlrev_b32_e32 v78, 16, v75
	v_and_b32_e32 v75, 0xffff0000, v83
	v_lshlrev_b32_e32 v74, 16, v83
	v_and_b32_e32 v83, 0xffff0000, v76
	v_lshlrev_b32_e32 v82, 16, v80
	v_and_b32_e32 v101, 0xffff0000, v80
	v_lshlrev_b32_e32 v100, 16, v76
	v_and_b32_e32 v105, 0xffff0000, v77
	v_lshlrev_b32_e32 v80, 16, v77
	v_and_b32_e32 v77, 0xffff0000, v85
	v_lshlrev_b32_e32 v76, 16, v85
	v_sub_f32_e32 v85, v107, v108
	v_mul_f32_e32 v61, 0x3fb8aa3b, v61
	v_mul_f32_e32 v84, 0x3fb8aa3b, v84
	v_mul_f32_e32 v106, 0x3fb8aa3b, v85
	v_exp_f32_e32 v85, v61
	v_exp_f32_e32 v84, v84
	v_exp_f32_e32 v61, v106
	v_lshlrev_b32_e32 v98, 16, v79
	v_and_b32_e32 v79, 0xffff0000, v79
	v_add_f32_e32 v106, v85, v84
	v_add_f32_e32 v106, v61, v106
	v_div_scale_f32 v107, s[10:11], v106, v106, 1.0
	v_rcp_f32_e32 v109, v107
	v_div_scale_f32 v108, vcc, 1.0, v106, 1.0
	v_lshlrev_b32_e32 v104, 16, v81
	v_fma_f32 v110, -v107, v109, 1.0
	v_fmac_f32_e32 v109, v110, v109
	v_mul_f32_e32 v110, v108, v109
	v_fma_f32 v111, -v107, v110, v108
	v_fmac_f32_e32 v110, v111, v109
	v_fma_f32 v107, -v107, v110, v108
	v_div_fmas_f32 v107, v107, v109, v110
	v_div_fixup_f32 v106, v107, v106, 1.0
	v_and_b32_e32 v81, 0xffff0000, v81
	v_pk_mul_f32 v[84:85], v[84:85], v[106:107] op_sel_hi:[1,0]
	v_mul_f32_e32 v108, v61, v106
	v_pk_mul_f32 v[94:95], v[84:85], v[94:95] op_sel:[1,0] op_sel_hi:[0,1]
	v_pk_mul_f32 v[78:79], v[84:85], v[78:79] op_sel:[1,0] op_sel_hi:[0,1]
	v_pk_mul_f32 v[100:101], v[84:85], v[100:101] op_sel:[1,0] op_sel_hi:[0,1]
	v_pk_mul_f32 v[80:81], v[84:85], v[80:81] op_sel:[1,0] op_sel_hi:[0,1]
	v_pk_fma_f32 v[72:73], v[84:85], v[72:73], v[94:95]
	v_pk_fma_f32 v[78:79], v[84:85], v[98:99], v[78:79]
	v_pk_fma_f32 v[82:83], v[84:85], v[82:83], v[100:101]
	v_pk_fma_f32 v[80:81], v[84:85], v[104:105], v[80:81]
	v_pk_fma_f32 v[72:73], v[108:109], v[96:97], v[72:73] op_sel_hi:[0,1,1]
	v_pk_fma_f32 v[74:75], v[108:109], v[74:75], v[78:79] op_sel_hi:[0,1,1]
	v_pk_fma_f32 v[78:79], v[108:109], v[102:103], v[82:83] op_sel_hi:[0,1,1]
	v_pk_fma_f32 v[76:77], v[108:109], v[76:77], v[80:81] op_sel_hi:[0,1,1]
	v_pk_mul_f32 v[72:73], v[72:73], v[86:87]
	v_pk_mul_f32 v[74:75], v[74:75], v[88:89]
	v_pk_mul_f32 v[78:79], v[78:79], v[70:71]
	v_pk_mul_f32 v[76:77], v[76:77], v[92:93]
	v_cvt_pk_bf16_f32 v70, v72, v73
	v_cvt_pk_bf16_f32 v71, v74, v75
	v_cvt_pk_bf16_f32 v72, v78, v79
	v_cvt_pk_bf16_f32 v73, v76, v77
	global_store_dwordx4 v[90:91], v[70:73], off
	s_branch .Lmg_top
.Lmg_tail:
	v_cmp_lt_i32_e32 vcc, s9, v0
	s_or_b64 s[2:3], vcc, s[2:3]
	s_andn2_b64 exec, exec, s[2:3]
	s_cbranch_execz .LBB0_1772
